# v29 + proj chain epilogue: counted vmcnt(15..0) waits so each multiply group starts when its own gate load lands (strategy 1: counted waits)
# speedup vs baseline: 1.0061x; 1.0061x over previous
;   DI bool operator()(f4 (&acc)[2][2][4][2], const GUnit& u, int wr, int wc, int fr, int fq) const {
;     ...
;     const char* gp = (const char*)(gb + (size_t)((u.pm - pm0) * 256 + wr * 64) * 4096 + br * 1024 + u.pn * 256 + wc * 32);
;     const unsigned glo = (unsigned)(fr * 4096 + 8 * fq) * 2u;
;     h8 gq[2][4][2];
; #pragma unroll
;     for (int ai = 0; ai < 2; ++ai)
; #pragma unroll
;       for (int m = 0; m < 4; ++m)
; #pragma unroll
;         for (int bj = 0; bj < 2; ++bj) gq[ai][m][bj] = *(const h8*)(gp + ((size_t)(ai * 128 + m * 16) * 4096 + bj * 128) * 2 + glo);
; #pragma unroll
;     for (int ai = 0; ai < 2; ++ai)
; #pragma unroll
;       for (int m = 0; m < 4; ++m)
; #pragma unroll
;         for (int bj = 0; bj < 2; ++bj)
; #pragma unroll
;           for (int j = 0; j < 4; ++j) { acc[ai][bj][m][0][j] *= (float)gq[ai][m][bj][j]; acc[ai][bj][m][1][j] *= (float)gq[ai][m][bj][4 + j]; }
.LBB0_2356:
	s_sub_i32 s8, s61, s90
	s_lshl_b32 s8, s8, 8
	s_add_i32 s8, s8, s24
	s_ashr_i32 s9, s8, 31
	s_lshl_b64 s[8:9], s[8:9], 13
	s_add_u32 s10, s76, s8
	s_addc_u32 s11, s77, s9
	s_lshl_b32 s8, s68, 10
	s_ashr_i32 s9, s8, 31
	s_lshl_b64 s[8:9], s[8:9], 1
	s_add_u32 s10, s10, s8
	s_addc_u32 s11, s11, s9
	s_lshl_b32 s8, s84, 8
	s_ashr_i32 s9, s8, 31
	s_lshl_b64 s[8:9], s[8:9], 1
	s_add_u32 s10, s10, s8
	s_addc_u32 s11, s11, s9
	s_lshl_b32 s46, s25, 1
	s_add_u32 s10, s10, s46
	s_addc_u32 s11, s11, 0
	v_lshl_add_u64 v[2:3], s[10:11], 0, v[194:195]
	global_load_dwordx4 v[202:205], v[2:3], off
	global_load_dwordx4 v[206:209], v[2:3], off offset:256
	v_add_co_u32_e32 v132, vcc, s51, v2
	s_cmp_gt_i32 s68, 2
	s_nop 0
	v_addc_co_u32_e32 v133, vcc, 0, v3, vcc
	global_load_dwordx4 v[210:213], v[132:133], off
	global_load_dwordx4 v[180:183], v[132:133], off offset:256
	v_add_co_u32_e32 v132, vcc, s47, v2
	s_cselect_b64 s[10:11], -1, 0
	s_nop 0
	v_addc_co_u32_e32 v133, vcc, 0, v3, vcc
	global_load_dwordx4 v[176:179], v[132:133], off
	global_load_dwordx4 v[172:175], v[132:133], off offset:256
	v_add_co_u32_e32 v132, vcc, s72, v2
	s_cmp_lt_i32 s68, 3
	s_nop 0
	v_addc_co_u32_e32 v133, vcc, 0, v3, vcc
	global_load_dwordx4 v[168:171], v[132:133], off
	global_load_dwordx4 v[164:167], v[132:133], off offset:256
	v_add_co_u32_e32 v132, vcc, s64, v2
	s_nop 1
	v_addc_co_u32_e32 v133, vcc, 0, v3, vcc
	global_load_dwordx4 v[160:163], v[132:133], off
	global_load_dwordx4 v[156:159], v[132:133], off offset:256
	v_add_co_u32_e32 v132, vcc, s67, v2
	s_nop 1
	v_addc_co_u32_e32 v133, vcc, 0, v3, vcc
	global_load_dwordx4 v[152:155], v[132:133], off
	global_load_dwordx4 v[148:151], v[132:133], off offset:256
	v_add_co_u32_e32 v132, vcc, s48, v2
	s_nop 1
	v_addc_co_u32_e32 v133, vcc, 0, v3, vcc
	v_add_co_u32_e32 v2, vcc, s49, v2
	global_load_dwordx4 v[144:147], v[132:133], off
	global_load_dwordx4 v[136:139], v[132:133], off offset:256
	v_addc_co_u32_e32 v3, vcc, 0, v3, vcc
	global_load_dwordx4 v[140:143], v[2:3], off
	global_load_dwordx4 v[132:135], v[2:3], off offset:256
	s_waitcnt vmcnt(15)
	v_cvt_f32_f16_e32 v2, v202
	v_cvt_f32_f16_sdwa v3, v202 dst_sel:DWORD dst_unused:UNUSED_PAD src0_sel:WORD_1
	v_pk_mul_f32 v[128:129], v[128:129], v[2:3]
	v_cvt_f32_f16_e32 v2, v204
	v_cvt_f32_f16_sdwa v3, v204 dst_sel:DWORD dst_unused:UNUSED_PAD src0_sel:WORD_1
	v_pk_mul_f32 v[124:125], v[124:125], v[2:3]
	v_cvt_f32_f16_e32 v2, v203
	v_cvt_f32_f16_sdwa v3, v203 dst_sel:DWORD dst_unused:UNUSED_PAD src0_sel:WORD_1
	v_pk_mul_f32 v[130:131], v[130:131], v[2:3]
	v_cvt_f32_f16_e32 v2, v205
	v_cvt_f32_f16_sdwa v3, v205 dst_sel:DWORD dst_unused:UNUSED_PAD src0_sel:WORD_1
	v_pk_mul_f32 v[126:127], v[126:127], v[2:3]
	s_waitcnt vmcnt(14)
	v_cvt_f32_f16_e32 v2, v206
	v_cvt_f32_f16_sdwa v3, v206 dst_sel:DWORD dst_unused:UNUSED_PAD src0_sel:WORD_1
	v_pk_mul_f32 v[96:97], v[96:97], v[2:3]
	v_cvt_f32_f16_e32 v2, v208
	v_cvt_f32_f16_sdwa v3, v208 dst_sel:DWORD dst_unused:UNUSED_PAD src0_sel:WORD_1
	v_pk_mul_f32 v[92:93], v[92:93], v[2:3]
	v_cvt_f32_f16_e32 v2, v207
	v_cvt_f32_f16_sdwa v3, v207 dst_sel:DWORD dst_unused:UNUSED_PAD src0_sel:WORD_1
	v_pk_mul_f32 v[98:99], v[98:99], v[2:3]
	v_cvt_f32_f16_e32 v2, v209
	v_cvt_f32_f16_sdwa v3, v209 dst_sel:DWORD dst_unused:UNUSED_PAD src0_sel:WORD_1
	v_pk_mul_f32 v[94:95], v[94:95], v[2:3]
	s_waitcnt vmcnt(13)
	v_cvt_f32_f16_e32 v2, v210
	v_cvt_f32_f16_sdwa v3, v210 dst_sel:DWORD dst_unused:UNUSED_PAD src0_sel:WORD_1
	v_pk_mul_f32 v[120:121], v[120:121], v[2:3]
	v_cvt_f32_f16_e32 v2, v212
	v_cvt_f32_f16_sdwa v3, v212 dst_sel:DWORD dst_unused:UNUSED_PAD src0_sel:WORD_1
	v_pk_mul_f32 v[116:117], v[116:117], v[2:3]
	v_cvt_f32_f16_e32 v2, v211
	v_cvt_f32_f16_sdwa v3, v211 dst_sel:DWORD dst_unused:UNUSED_PAD src0_sel:WORD_1
	v_pk_mul_f32 v[122:123], v[122:123], v[2:3]
	v_cvt_f32_f16_e32 v2, v213
	v_cvt_f32_f16_sdwa v3, v213 dst_sel:DWORD dst_unused:UNUSED_PAD src0_sel:WORD_1
	v_pk_mul_f32 v[118:119], v[118:119], v[2:3]
	s_waitcnt vmcnt(12)
	v_cvt_f32_f16_e32 v2, v180
	v_cvt_f32_f16_sdwa v3, v180 dst_sel:DWORD dst_unused:UNUSED_PAD src0_sel:WORD_1
	v_pk_mul_f32 v[88:89], v[88:89], v[2:3]
	v_cvt_f32_f16_e32 v2, v182
	v_cvt_f32_f16_sdwa v3, v182 dst_sel:DWORD dst_unused:UNUSED_PAD src0_sel:WORD_1
	v_pk_mul_f32 v[84:85], v[84:85], v[2:3]
	v_cvt_f32_f16_e32 v2, v181
	v_cvt_f32_f16_sdwa v3, v181 dst_sel:DWORD dst_unused:UNUSED_PAD src0_sel:WORD_1
	v_pk_mul_f32 v[90:91], v[90:91], v[2:3]
	v_cvt_f32_f16_e32 v2, v183
	v_cvt_f32_f16_sdwa v3, v183 dst_sel:DWORD dst_unused:UNUSED_PAD src0_sel:WORD_1
	v_pk_mul_f32 v[86:87], v[86:87], v[2:3]
	s_waitcnt vmcnt(11)
	v_cvt_f32_f16_e32 v2, v176
	v_cvt_f32_f16_sdwa v3, v176 dst_sel:DWORD dst_unused:UNUSED_PAD src0_sel:WORD_1
	v_pk_mul_f32 v[112:113], v[112:113], v[2:3]
	v_cvt_f32_f16_e32 v2, v178
	v_cvt_f32_f16_sdwa v3, v178 dst_sel:DWORD dst_unused:UNUSED_PAD src0_sel:WORD_1
	v_pk_mul_f32 v[108:109], v[108:109], v[2:3]
	v_cvt_f32_f16_e32 v2, v177
	v_cvt_f32_f16_sdwa v3, v177 dst_sel:DWORD dst_unused:UNUSED_PAD src0_sel:WORD_1
	v_pk_mul_f32 v[114:115], v[114:115], v[2:3]
	v_cvt_f32_f16_e32 v2, v179
	v_cvt_f32_f16_sdwa v3, v179 dst_sel:DWORD dst_unused:UNUSED_PAD src0_sel:WORD_1
	v_pk_mul_f32 v[110:111], v[110:111], v[2:3]
	s_waitcnt vmcnt(10)
	v_cvt_f32_f16_e32 v2, v172
	v_cvt_f32_f16_sdwa v3, v172 dst_sel:DWORD dst_unused:UNUSED_PAD src0_sel:WORD_1
	v_pk_mul_f32 v[80:81], v[80:81], v[2:3]
	v_cvt_f32_f16_e32 v2, v174
	v_cvt_f32_f16_sdwa v3, v174 dst_sel:DWORD dst_unused:UNUSED_PAD src0_sel:WORD_1
	v_pk_mul_f32 v[76:77], v[76:77], v[2:3]
	v_cvt_f32_f16_e32 v2, v173
	v_cvt_f32_f16_sdwa v3, v173 dst_sel:DWORD dst_unused:UNUSED_PAD src0_sel:WORD_1
	v_pk_mul_f32 v[82:83], v[82:83], v[2:3]
	v_cvt_f32_f16_e32 v2, v175
	v_cvt_f32_f16_sdwa v3, v175 dst_sel:DWORD dst_unused:UNUSED_PAD src0_sel:WORD_1
	v_pk_mul_f32 v[78:79], v[78:79], v[2:3]
	s_waitcnt vmcnt(9)
;   DI bool operator()(f4 (&acc)[2][2][4][2], const GUnit& u, int wr, int wc, int fr, int fq) const {
;     ...
;     for (int ai = 0; ai < 2; ++ai)
; #pragma unroll
;       for (int m = 0; m < 4; ++m)
; #pragma unroll
;         for (int bj = 0; bj < 2; ++bj)
; #pragma unroll
;           for (int j = 0; j < 4; ++j) { acc[ai][bj][m][0][j] *= (float)gq[ai][m][bj][j]; acc[ai][bj][m][1][j] *= (float)gq[ai][m][bj][4 + j]; }
;     if (br < 3) return true;
;     char* mp = (char*)(mbuf + (size_t)(row0_of(u.pm, mode) + wr * 64) * 1024 + u.pn * 256 + wc * 32);
	v_cvt_f32_f16_e32 v2, v168
	v_cvt_f32_f16_sdwa v3, v168 dst_sel:DWORD dst_unused:UNUSED_PAD src0_sel:WORD_1
	v_pk_mul_f32 v[104:105], v[104:105], v[2:3]
	v_cvt_f32_f16_e32 v2, v170
	v_cvt_f32_f16_sdwa v3, v170 dst_sel:DWORD dst_unused:UNUSED_PAD src0_sel:WORD_1
	v_pk_mul_f32 v[100:101], v[100:101], v[2:3]
	v_cvt_f32_f16_e32 v2, v169
	v_cvt_f32_f16_sdwa v3, v169 dst_sel:DWORD dst_unused:UNUSED_PAD src0_sel:WORD_1
	v_pk_mul_f32 v[106:107], v[106:107], v[2:3]
	v_cvt_f32_f16_e32 v2, v171
	v_cvt_f32_f16_sdwa v3, v171 dst_sel:DWORD dst_unused:UNUSED_PAD src0_sel:WORD_1
	v_pk_mul_f32 v[102:103], v[102:103], v[2:3]
	s_waitcnt vmcnt(8)
	v_cvt_f32_f16_e32 v2, v164
	v_cvt_f32_f16_sdwa v3, v164 dst_sel:DWORD dst_unused:UNUSED_PAD src0_sel:WORD_1
	v_pk_mul_f32 v[72:73], v[72:73], v[2:3]
	v_cvt_f32_f16_e32 v2, v166
	v_cvt_f32_f16_sdwa v3, v166 dst_sel:DWORD dst_unused:UNUSED_PAD src0_sel:WORD_1
	v_pk_mul_f32 v[68:69], v[68:69], v[2:3]
	v_cvt_f32_f16_e32 v2, v165
	v_cvt_f32_f16_sdwa v3, v165 dst_sel:DWORD dst_unused:UNUSED_PAD src0_sel:WORD_1
	v_pk_mul_f32 v[74:75], v[74:75], v[2:3]
	v_cvt_f32_f16_e32 v2, v167
	v_cvt_f32_f16_sdwa v3, v167 dst_sel:DWORD dst_unused:UNUSED_PAD src0_sel:WORD_1
	v_pk_mul_f32 v[70:71], v[70:71], v[2:3]
	s_waitcnt vmcnt(7)
	v_cvt_f32_f16_e32 v2, v160
	v_cvt_f32_f16_sdwa v3, v160 dst_sel:DWORD dst_unused:UNUSED_PAD src0_sel:WORD_1
	v_pk_mul_f32 v[64:65], v[64:65], v[2:3]
	v_cvt_f32_f16_e32 v2, v162
	v_cvt_f32_f16_sdwa v3, v162 dst_sel:DWORD dst_unused:UNUSED_PAD src0_sel:WORD_1
	v_pk_mul_f32 v[60:61], v[60:61], v[2:3]
	v_cvt_f32_f16_e32 v2, v161
	v_cvt_f32_f16_sdwa v3, v161 dst_sel:DWORD dst_unused:UNUSED_PAD src0_sel:WORD_1
	v_pk_mul_f32 v[66:67], v[66:67], v[2:3]
	v_cvt_f32_f16_e32 v2, v163
	v_cvt_f32_f16_sdwa v3, v163 dst_sel:DWORD dst_unused:UNUSED_PAD src0_sel:WORD_1
	v_pk_mul_f32 v[62:63], v[62:63], v[2:3]
	s_waitcnt vmcnt(6)
	v_cvt_f32_f16_e32 v2, v156
	v_cvt_f32_f16_sdwa v3, v156 dst_sel:DWORD dst_unused:UNUSED_PAD src0_sel:WORD_1
	v_pk_mul_f32 v[32:33], v[32:33], v[2:3]
	v_cvt_f32_f16_e32 v2, v158
	v_cvt_f32_f16_sdwa v3, v158 dst_sel:DWORD dst_unused:UNUSED_PAD src0_sel:WORD_1
	v_pk_mul_f32 v[28:29], v[28:29], v[2:3]
	v_cvt_f32_f16_e32 v2, v157
	v_cvt_f32_f16_sdwa v3, v157 dst_sel:DWORD dst_unused:UNUSED_PAD src0_sel:WORD_1
	v_pk_mul_f32 v[34:35], v[34:35], v[2:3]
	v_cvt_f32_f16_e32 v2, v159
	v_cvt_f32_f16_sdwa v3, v159 dst_sel:DWORD dst_unused:UNUSED_PAD src0_sel:WORD_1
	v_pk_mul_f32 v[30:31], v[30:31], v[2:3]
	s_waitcnt vmcnt(5)
	v_cvt_f32_f16_e32 v2, v152
	v_cvt_f32_f16_sdwa v3, v152 dst_sel:DWORD dst_unused:UNUSED_PAD src0_sel:WORD_1
	v_pk_mul_f32 v[56:57], v[56:57], v[2:3]
	v_cvt_f32_f16_e32 v2, v154
	v_cvt_f32_f16_sdwa v3, v154 dst_sel:DWORD dst_unused:UNUSED_PAD src0_sel:WORD_1
	v_pk_mul_f32 v[52:53], v[52:53], v[2:3]
	v_cvt_f32_f16_e32 v2, v153
	v_cvt_f32_f16_sdwa v3, v153 dst_sel:DWORD dst_unused:UNUSED_PAD src0_sel:WORD_1
	v_pk_mul_f32 v[58:59], v[58:59], v[2:3]
	v_cvt_f32_f16_e32 v2, v155
	v_cvt_f32_f16_sdwa v3, v155 dst_sel:DWORD dst_unused:UNUSED_PAD src0_sel:WORD_1
	v_pk_mul_f32 v[54:55], v[54:55], v[2:3]
	s_waitcnt vmcnt(4)
	v_cvt_f32_f16_e32 v2, v148
	v_cvt_f32_f16_sdwa v3, v148 dst_sel:DWORD dst_unused:UNUSED_PAD src0_sel:WORD_1
	v_pk_mul_f32 v[24:25], v[24:25], v[2:3]
	v_cvt_f32_f16_e32 v2, v150
	v_cvt_f32_f16_sdwa v3, v150 dst_sel:DWORD dst_unused:UNUSED_PAD src0_sel:WORD_1
	v_pk_mul_f32 v[20:21], v[20:21], v[2:3]
	v_cvt_f32_f16_e32 v2, v149
	v_cvt_f32_f16_sdwa v3, v149 dst_sel:DWORD dst_unused:UNUSED_PAD src0_sel:WORD_1
	v_pk_mul_f32 v[26:27], v[26:27], v[2:3]
	v_cvt_f32_f16_e32 v2, v151
	v_cvt_f32_f16_sdwa v3, v151 dst_sel:DWORD dst_unused:UNUSED_PAD src0_sel:WORD_1
	v_pk_mul_f32 v[22:23], v[22:23], v[2:3]
	s_waitcnt vmcnt(3)
	v_cvt_f32_f16_e32 v2, v144
	v_cvt_f32_f16_sdwa v3, v144 dst_sel:DWORD dst_unused:UNUSED_PAD src0_sel:WORD_1
	v_pk_mul_f32 v[48:49], v[48:49], v[2:3]
	v_cvt_f32_f16_e32 v2, v146
	v_cvt_f32_f16_sdwa v3, v146 dst_sel:DWORD dst_unused:UNUSED_PAD src0_sel:WORD_1
	v_pk_mul_f32 v[44:45], v[44:45], v[2:3]
	v_cvt_f32_f16_e32 v2, v145
	v_cvt_f32_f16_sdwa v3, v145 dst_sel:DWORD dst_unused:UNUSED_PAD src0_sel:WORD_1
	v_pk_mul_f32 v[50:51], v[50:51], v[2:3]
	v_cvt_f32_f16_e32 v2, v147
	v_cvt_f32_f16_sdwa v3, v147 dst_sel:DWORD dst_unused:UNUSED_PAD src0_sel:WORD_1
	v_pk_mul_f32 v[46:47], v[46:47], v[2:3]
	s_waitcnt vmcnt(2)
	v_cvt_f32_f16_e32 v2, v136
	v_cvt_f32_f16_sdwa v3, v136 dst_sel:DWORD dst_unused:UNUSED_PAD src0_sel:WORD_1
	v_pk_mul_f32 v[16:17], v[16:17], v[2:3]
	v_cvt_f32_f16_e32 v2, v138
	v_cvt_f32_f16_sdwa v3, v138 dst_sel:DWORD dst_unused:UNUSED_PAD src0_sel:WORD_1
	v_pk_mul_f32 v[12:13], v[12:13], v[2:3]
	v_cvt_f32_f16_e32 v2, v137
	v_cvt_f32_f16_sdwa v3, v137 dst_sel:DWORD dst_unused:UNUSED_PAD src0_sel:WORD_1
	v_pk_mul_f32 v[18:19], v[18:19], v[2:3]
	v_cvt_f32_f16_e32 v2, v139
	v_cvt_f32_f16_sdwa v3, v139 dst_sel:DWORD dst_unused:UNUSED_PAD src0_sel:WORD_1
	v_pk_mul_f32 v[14:15], v[14:15], v[2:3]
	s_waitcnt vmcnt(1)
	v_cvt_f32_f16_e32 v2, v140
	v_cvt_f32_f16_sdwa v3, v140 dst_sel:DWORD dst_unused:UNUSED_PAD src0_sel:WORD_1
	v_pk_mul_f32 v[40:41], v[40:41], v[2:3]
	v_cvt_f32_f16_e32 v2, v142
	v_cvt_f32_f16_sdwa v3, v142 dst_sel:DWORD dst_unused:UNUSED_PAD src0_sel:WORD_1
	v_pk_mul_f32 v[36:37], v[36:37], v[2:3]
	v_cvt_f32_f16_e32 v2, v141
	v_cvt_f32_f16_sdwa v3, v141 dst_sel:DWORD dst_unused:UNUSED_PAD src0_sel:WORD_1
	v_pk_mul_f32 v[42:43], v[42:43], v[2:3]
	v_cvt_f32_f16_e32 v2, v143
	v_cvt_f32_f16_sdwa v3, v143 dst_sel:DWORD dst_unused:UNUSED_PAD src0_sel:WORD_1
	v_pk_mul_f32 v[38:39], v[38:39], v[2:3]
	s_waitcnt vmcnt(0)
	v_cvt_f32_f16_e32 v2, v132
	v_cvt_f32_f16_sdwa v3, v132 dst_sel:DWORD dst_unused:UNUSED_PAD src0_sel:WORD_1
	v_pk_mul_f32 v[8:9], v[8:9], v[2:3]
	v_cvt_f32_f16_e32 v2, v134
	v_cvt_f32_f16_sdwa v3, v134 dst_sel:DWORD dst_unused:UNUSED_PAD src0_sel:WORD_1
	v_pk_mul_f32 v[4:5], v[4:5], v[2:3]
	v_cvt_f32_f16_e32 v2, v133
	v_cvt_f32_f16_sdwa v3, v133 dst_sel:DWORD dst_unused:UNUSED_PAD src0_sel:WORD_1
	v_pk_mul_f32 v[10:11], v[10:11], v[2:3]
	v_cvt_f32_f16_e32 v2, v135
	v_cvt_f32_f16_sdwa v3, v135 dst_sel:DWORD dst_unused:UNUSED_PAD src0_sel:WORD_1
	v_pk_mul_f32 v[6:7], v[6:7], v[2:3]
	s_cbranch_scc1 .LBB0_2362
	s_mov_b64 s[12:13], -1
	s_and_b64 vcc, exec, s[36:37]
	s_cbranch_vccz .LBB0_2359
	s_mul_i32 s12, s61, 0x900
	s_add_i32 s68, s12, 0x800
	s_mov_b64 s[12:13], 0
